# write-through stores in merge/w_out/down GEMM phases and no L2 writeback at the barriers that follow them
# baseline (speedup 1.0000x reference)
; __device__ __forceinline__ unsigned xb_add(unsigned* p, unsigned v) { return __hip_atomic_fetch_add(p, v, __ATOMIC_RELAXED, __HIP_MEMORY_SCOPE_AGENT); }
; __device__ __forceinline__ void xcd_barrier(const XcdBarrier& b) {
;     ...
;         const unsigned old = xb_add(&bar[XB_XSUB(b.x)], 1u);
;         const unsigned gen = old / nloc;
;         if (old + 1u == (gen + 1u) * nloc) {
;             __builtin_amdgcn_fence(__ATOMIC_RELEASE, "agent");
;             asm volatile("s_waitcnt vmcnt(0)" ::: "memory");
;             const unsigned og = xb_add(&bar[XB_TOP], 1u);
.LBB0_547:
	s_andn2_saveexec_b64 s[10:11], s[10:11]
	s_cbranch_execz .LBB0_567
	s_mov_b64 s[10:11], exec
	s_mov_b32 s2, 0x4c260
	s_lshr_b32 s2, s2, s80
	s_and_b32 s2, s2, 1
	s_cbranch_scc1 .Lbar_nowb
	buffer_wbl2 sc1
.Lbar_nowb:
	buffer_inv sc1
	s_waitcnt lgkmcnt(0)
	s_waitcnt vmcnt(0)
	v_mbcnt_lo_u32_b32 v2, s10, 0
	v_mbcnt_hi_u32_b32 v2, s11, v2
	v_cmp_eq_u32_e32 vcc, 0, v2
	s_and_saveexec_b64 s[12:13], vcc
	s_cbranch_execz .LBB0_550
	s_bcnt1_i32_b64 s2, s[10:11]
	v_mov_b32_e32 v3, s2
	v_mov_b32_e32 v4, 0x32c03000
	global_atomic_add v3, v4, v3, s[6:7] offset:1024 sc0
